# P3 unit order per workgroup class (vb mod 7): FFT2 burst placed between attention units so few WGs stream FFT2 at once
# speedup vs baseline: 1.1040x; 1.0099x over previous
.LBB0_296:
	s_or_b64 exec, exec, s[0:1]
	s_waitcnt lgkmcnt(0)
	v_lshlrev_b32_e32 v0, 2, v190
	s_barrier
	global_load_dword v1, v0, s[20:21]
	global_load_dword v2, v0, s[22:23]
	v_mbcnt_hi_u32_b32 v0, -1, v218
	v_and_b32_e32 v3, 64, v0
	v_xor_b32_e32 v4, 1, v0
	v_add_u32_e32 v3, 64, v3
	v_cmp_lt_i32_e32 vcc, v4, v3
	v_xor_b32_e32 v5, 2, v0
	v_xor_b32_e32 v6, 4, v0
	v_cndmask_b32_e32 v4, v0, v4, vcc
	v_lshlrev_b32_e32 v142, 2, v4
	v_cmp_lt_i32_e32 vcc, v5, v3
	v_xor_b32_e32 v7, 8, v0
	v_xor_b32_e32 v8, 16, v0
	v_cndmask_b32_e32 v5, v0, v5, vcc
	v_lshlrev_b32_e32 v143, 2, v5
	v_cmp_lt_i32_e32 vcc, v6, v3
	v_xor_b32_e32 v9, 32, v0
	s_add_u32 s0, s42, 0x11800000
	v_cndmask_b32_e32 v6, v0, v6, vcc
	v_lshlrev_b32_e32 v144, 2, v6
	v_cmp_lt_i32_e32 vcc, v7, v3
	s_addc_u32 s1, s43, 0
	v_mov_b32_e32 v99, 0
	v_cndmask_b32_e32 v6, v0, v7, vcc
	v_lshlrev_b32_e32 v145, 2, v6
	v_cmp_lt_i32_e32 vcc, v8, v3
	s_mov_b32 s17, 0
	s_cmpk_lt_i32 s75, 0xc00
	v_cndmask_b32_e32 v6, v0, v8, vcc
	v_lshlrev_b32_e32 v146, 2, v6
	v_cmp_lt_i32_e32 vcc, v9, v3
	s_waitcnt vmcnt(1)
	v_and_b32_e32 v4, 0x7fffffff, v1
	s_waitcnt vmcnt(0)
	v_and_b32_e32 v10, 0x7fffffff, v2
	ds_bpermute_b32 v4, v142, v4
	ds_bpermute_b32 v10, v142, v10
	v_max_f32_e64 v1, |v1|, |v1|
	v_max_f32_e64 v2, |v2|, |v2|
	v_cndmask_b32_e32 v0, v0, v9, vcc
	s_waitcnt lgkmcnt(1)
	v_max_f32_e32 v4, v4, v4
	s_waitcnt lgkmcnt(0)
	v_max_f32_e32 v5, v10, v10
	v_max_f32_e32 v1, v1, v4
	v_max_f32_e32 v2, v2, v5
	ds_bpermute_b32 v4, v143, v1
	ds_bpermute_b32 v5, v143, v2
	v_lshlrev_b32_e32 v147, 2, v0
	s_waitcnt lgkmcnt(1)
	v_max_f32_e32 v4, v4, v4
	s_waitcnt lgkmcnt(0)
	v_max_f32_e32 v5, v5, v5
	v_max_f32_e32 v1, v1, v4
	v_max_f32_e32 v2, v2, v5
	ds_bpermute_b32 v4, v144, v1
	ds_bpermute_b32 v5, v144, v2
	s_waitcnt lgkmcnt(1)
	v_max_f32_e32 v4, v4, v4
	s_waitcnt lgkmcnt(0)
	v_max_f32_e32 v5, v5, v5
	v_max_f32_e32 v1, v1, v4
	v_max_f32_e32 v2, v2, v5
	ds_bpermute_b32 v4, v145, v1
	ds_bpermute_b32 v5, v145, v2
	s_waitcnt lgkmcnt(1)
	v_max_f32_e32 v4, v4, v4
	s_waitcnt lgkmcnt(0)
	v_max_f32_e32 v5, v5, v5
	v_max_f32_e32 v1, v1, v4
	v_max_f32_e32 v2, v2, v5
	ds_bpermute_b32 v4, v146, v1
	ds_bpermute_b32 v5, v146, v2
	s_waitcnt lgkmcnt(1)
	v_max_f32_e32 v0, v4, v4
	s_waitcnt lgkmcnt(0)
	v_max_f32_e32 v3, v5, v5
	v_max_f32_e32 v0, v1, v0
	v_max_f32_e32 v1, v2, v3
	ds_bpermute_b32 v2, v147, v0
	ds_bpermute_b32 v3, v147, v1
	s_waitcnt lgkmcnt(1)
	v_max_f32_e32 v2, v2, v2
	s_waitcnt lgkmcnt(0)
	v_max_f32_e32 v3, v3, v3
	v_max_f32_e32 v0, v0, v2
	v_max_f32_e32 v1, v1, v3
	v_mul_f32_e32 v0, 0x4138aa3b, v0
	v_mul_f32_e32 v0, v0, v1
	s_nop 0
	v_readfirstlane_b32 s2, v0
	s_cbranch_scc0 .LBB0_320
	v_mov_b32_e32 v0, 0x42200000
	s_lshl_b32 s4, s74, 12
	v_lshrrev_b32_e32 v148, 3, v191
	v_cmp_nlt_f32_e64 s[2:3], s2, v0
	s_lshl_b32 s18, s74, 5
	s_add_i32 s4, s4, 0
	s_mov_b32 s19, s17
	v_xor_b32_e32 v0, v148, v191
	s_add_i32 s11, s4, 0x10000
	s_lshl_b64 s[4:5], s[18:19], 2
	v_lshlrev_b32_e32 v0, 4, v0
	s_add_u32 s4, s26, s4
	v_and_b32_e32 v0, 48, v0
	v_lshlrev_b32_e32 v2, 7, v148
	v_xor_b32_e32 v3, v212, v191
	s_movk_i32 s6, 0x70
	s_addc_u32 s5, s27, s5
	v_lshlrev_b32_e32 v98, 4, v197
	v_add_u32_e32 v4, s11, v0
	v_and_b32_e32 v0, 4, v191
	v_and_or_b32 v2, v3, s6, v2
	v_bfe_u32 v3, v191, 1, 3
	v_bitop3_b32 v14, v197, v219, 7 bitop3:0x78
	v_lshl_add_u64 v[100:101], s[4:5], 0, v[98:99]
	v_cmp_eq_u32_e64 s[4:5], 0, v0
	v_and_b32_e32 v0, 56, v220
	v_readlane_b32 s8, v254, 22
	v_lshlrev_b32_e32 v156, 4, v14
	v_bitop3_b32 v14, v197, v3, 2 bitop3:0x36
	v_add_u32_e32 v150, 0, v2
	v_lshlrev_b32_e32 v2, 7, v189
	v_lshlrev_b32_e32 v98, 1, v0
	v_readlane_b32 s9, v254, 23
	v_lshlrev_b32_e32 v157, 4, v14
	v_bitop3_b32 v14, v197, v3, 4 bitop3:0x36
	v_bitop3_b32 v3, v197, v3, 6 bitop3:0x36
	v_add_u32_e32 v151, 0, v2
	v_add_u32_e32 v5, s11, v2
	v_and_b32_e32 v2, 15, v191
	v_lshl_add_u64 v[102:103], s[8:9], 0, v[98:99]
	v_readlane_b32 s8, v254, 5
	v_lshlrev_b32_e32 v159, 4, v3
	v_bitop3_b32 v3, v197, v191, 15 bitop3:0x78
	v_mov_b32_e32 v195, v99
	v_readlane_b32 s9, v254, 6
	v_lshlrev_b32_e32 v158, 4, v14
	v_lshlrev_b32_e32 v14, 3, v3
	v_bitop3_b32 v3, v197, v2, 2 bitop3:0x36
	v_lshl_add_u64 v[106:107], s[8:9], 0, v[194:195]
	s_mov_b64 s[8:9], 0x1000
	v_lshlrev_b32_e32 v15, 3, v3
	v_bitop3_b32 v3, v197, v2, 4 bitop3:0x36
	v_lshl_add_u64 v[108:109], v[106:107], 0, s[8:9]
	s_mov_b64 s[8:9], 0x1400
	v_lshlrev_b32_e32 v16, 3, v3
	v_bitop3_b32 v3, v197, v2, 6 bitop3:0x36
	v_lshl_add_u64 v[110:111], v[106:107], 0, s[8:9]
	s_mov_b64 s[8:9], 0x1800
	v_lshlrev_b32_e32 v17, 3, v3
	v_bitop3_b32 v3, v197, v2, 8 bitop3:0x36
	v_lshl_add_u64 v[112:113], v[106:107], 0, s[8:9]
	s_mov_b64 s[8:9], 0x1c00
	v_lshlrev_b32_e32 v18, 3, v3
	v_bitop3_b32 v3, v197, v2, 10 bitop3:0x36
	v_lshrrev_b32_e32 v152, 3, v190
	v_lshl_add_u64 v[114:115], v[106:107], 0, s[8:9]
	s_mov_b64 s[8:9], 0x2000
	v_lshlrev_b32_e32 v19, 3, v3
	v_bitop3_b32 v3, v197, v2, 12 bitop3:0x36
	v_bitop3_b32 v2, v197, v2, 14 bitop3:0x36
	v_lshl_add_u64 v[116:117], v[106:107], 0, s[8:9]
	s_mov_b64 s[8:9], 0x2400
	v_lshlrev_b32_e32 v21, 3, v2
	v_and_b32_e32 v2, 0x70, v212
	v_or_b32_e32 v160, 8, v152
	v_lshl_add_u64 v[118:119], v[106:107], 0, s[8:9]
	s_mov_b64 s[8:9], 0x2800
	v_bitop3_b32 v23, v191, v2, 48 bitop3:0x6c
	v_lshrrev_b32_e32 v2, 1, v160
	v_lshl_add_u64 v[120:121], v[106:107], 0, s[8:9]
	s_mov_b64 s[8:9], 0x2c00
	v_xor_b32_e32 v2, v2, v191
	v_lshl_add_u64 v[122:123], v[106:107], 0, s[8:9]
	s_mov_b64 s[8:9], 0x3000
	v_lshlrev_b32_e32 v2, 4, v2
	v_or_b32_e32 v162, 24, v152
	v_lshl_add_u64 v[124:125], v[106:107], 0, s[8:9]
	s_mov_b64 s[8:9], 0x3400
	v_and_b32_e32 v25, 0x70, v2
	v_lshrrev_b32_e32 v2, 1, v162
	v_lshl_add_u64 v[126:127], v[106:107], 0, s[8:9]
	s_mov_b64 s[8:9], 0x3800
	v_xor_b32_e32 v2, v2, v191
	v_and_b32_e32 v6, 8, v191
	v_lshl_add_u64 v[104:105], s[0:1], 0, v[98:99]
	v_lshl_add_u64 v[128:129], v[106:107], 0, s[8:9]
	s_mov_b64 s[8:9], 0x3c00
	v_lshlrev_b32_e32 v2, 4, v2
	v_lshlrev_b32_e32 v98, 4, v217
	v_cmp_eq_u32_e64 s[6:7], 0, v6
	v_lshl_add_u64 v[130:131], v[106:107], 0, s[8:9]
	v_bitop3_b32 v6, v197, v191, 7 bitop3:0x78
	v_bitop3_b32 v7, v197, v217, 2 bitop3:0x36
	v_bitop3_b32 v8, v197, v217, 4 bitop3:0x36
	v_bitop3_b32 v9, v197, v217, 6 bitop3:0x36
	v_or_b32_e32 v153, 16, v193
	v_or_b32_e32 v154, 32, v193
	v_or_b32_e32 v155, 48, v193
	v_lshlrev_b32_e32 v20, 3, v3
	v_or_b32_e32 v161, 16, v152
	v_and_b32_e32 v28, 0x70, v2
	v_lshl_add_u64 v[2:3], s[42:43], 0, v[98:99]
	s_mov_b64 s[8:9], 0xac00100
	v_lshl_add_u32 v1, v189, 6, s11
	v_lshlrev_b32_e32 v6, 3, v6
	v_lshlrev_b32_e32 v7, 3, v7
	v_lshlrev_b32_e32 v8, 3, v8
	v_lshlrev_b32_e32 v9, 3, v9
	v_lshlrev_b32_e32 v10, 6, v193
	v_lshlrev_b32_e32 v11, 6, v153
	v_lshlrev_b32_e32 v12, 6, v154
	v_lshlrev_b32_e32 v13, 6, v155
	v_lshl_add_u32 v22, v152, 7, s11
	v_lshl_add_u32 v24, v160, 7, s11
	v_lshl_add_u32 v26, v161, 7, s11
	v_lshl_add_u32 v27, v162, 7, s11
	v_lshl_add_u64 v[132:133], v[2:3], 0, s[8:9]
	s_mov_b64 s[8:9], 0xa008000
	v_and_b32_e32 v149, 24, v220
	v_lshl_add_u64 v[134:135], v[2:3], 0, s[8:9]
	v_add_u32_e32 v163, v1, v6
	v_add_u32_e32 v164, v1, v7
	v_add_u32_e32 v165, v1, v8
	v_add_u32_e32 v166, v1, v9
	v_add_u32_e32 v167, v4, v10
	v_add_u32_e32 v168, v4, v11
	v_add_u32_e32 v169, v4, v12
	v_add_u32_e32 v170, v4, v13
	v_lshlrev_b32_e32 v136, 1, v0
	s_movk_i32 s11, 0x4000
	s_mov_b32 s19, 0x41000000
	s_mov_b64 s[20:21], 0x80
	v_add_u32_e32 v171, v5, v14
	v_add_u32_e32 v172, v5, v15
	v_add_u32_e32 v173, v5, v16
	v_add_u32_e32 v174, v5, v17
	v_add_u32_e32 v175, v5, v18
	v_add_u32_e32 v176, v5, v19
	v_add_u32_e32 v177, v5, v20
	v_add_u32_e32 v178, v5, v21
	v_add_u32_e32 v179, v22, v23
	v_add_u32_e32 v180, v24, v25
	v_add_u32_e32 v181, v26, v23
	v_add_u32_e32 v182, v27, v28
	v_mov_b32_e32 v183, 0x3c3504f3
	v_mov_b32_e32 v184, 0x3c800000
	s_mov_b32 s28, s75
	s_cmpk_lg_i32 s68, 0x100
	s_cbranch_scc1 .LBB0_300
	s_mul_i32 s45, s75, 0x2493
	s_lshr_b32 s45, s45, 16
	s_mul_i32 s45, s45, 7
	s_sub_u32 s45, s75, s45
	s_mov_b32 s44, -1
	s_branch .LBB0_299

.LBB0_299:
	s_cmpk_lg_i32 s68, 0x100
	s_cbranch_scc1 .Lp3_generic
	s_add_i32 s44, s44, 1
	s_cmp_ge_u32 s44, 12
	s_cbranch_scc1 .LBB0_320
	s_mov_b32 s28, s44
	s_cmp_lt_u32 s44, s45
	s_cbranch_scc1 .Lp3_set
	s_add_i32 s28, s44, 6
	s_sub_u32 s28, s28, s45
	s_cmp_lt_u32 s28, 12
	s_cbranch_scc1 .Lp3_set
	s_add_i32 s28, s44, -6
.Lp3_set:
	s_lshl_b32 s28, s28, 8
	s_add_i32 s28, s28, s75
	s_branch .LBB0_300
